# P6 scheduling: wave 7 of workgroups 0-175 does one prompt item plus one (slow, compiled-path) sample item; the prompt items it gives up become third items of other waves, so no wave chains two prompt
# speedup vs baseline: 1.0066x; 1.0066x over previous
; __device__ __forceinline__ unsigned pk2(float lo, float hi) { unsigned r; asm("v_cvt_pk_bf16_f32 %0, %1, %2" : "=v"(r) : "v"(lo), "v"(hi)); return r; }
; __global__ void __launch_bounds__(512, 2) fwd_kernel(Args args) {
;     ...
;     if (IN(6)) {
;         for (int it = gw; it < 264 * 22; it += NGW) act_item(it, UP, HALO, args.in[I_SCONV], args.in[I_WCONV], args.in[I_BCONV], out, lane);
;         for (int m = gw; m < T; m += NGW) {
;             const float* pp = (m < TP) ? args.in[I_PP] + (size_t)m * PLE : args.in[I_PS] + (size_t)(m - TP) * PLE;
;             const f32x4 v = ((const f32x4*)pp)[lane]; u32x2 wv; wv.x = pk2(v.x, v.y); wv.y = pk2(v.z, v.w); ((u32x2*)(PB + (size_t)m * PLE))[lane] = wv; }
.LBB0_767:
	s_cmp_lt_i32 s94, 7
	s_cselect_b64 s[6:7], -1, 0
	s_add_u32 s12, s92, 0x900000
	s_addc_u32 s13, s93, 0
	s_and_b64 s[28:29], s[6:7], s[0:1]
	s_andn2_b64 vcc, exec, s[28:29]
	s_cbranch_vccnz .LBB0_824
	s_cmpk_gt_i32 s34, 0x16af
	s_cbranch_scc1 .LBB0_819
	s_add_u32 s36, s42, 0x2c00
	s_addc_u32 s37, s43, 0
	s_add_u32 s38, s42, 0x5800
	s_addc_u32 s39, s43, 0
	s_add_u32 s40, s42, 0x8400
	s_addc_u32 s41, s43, 0
	s_add_u32 s46, s42, 0xb000
	s_addc_u32 s47, s43, 0
	s_add_u32 s54, s42, 0xdc00
	v_readlane_b32 s60, v237, 0
	s_addc_u32 s55, s43, 0
	v_readlane_b32 s61, v237, 1
	v_readlane_b32 s62, v237, 2
	v_readlane_b32 s63, v237, 3
	v_readlane_b32 s64, v237, 4
	v_readlane_b32 s65, v237, 5
	s_add_u32 s56, s44, 0x2c00
	v_readlane_b32 s66, v237, 6
	v_readlane_b32 s67, v237, 7
	s_mov_b64 s[60:61], s[64:65]
	s_addc_u32 s57, s45, 0
	s_mov_b64 s[62:63], s[66:67]
	s_add_u32 s3, s62, 0x5300000
	s_addc_u32 s21, s63, 0
	s_add_u32 s33, s62, 0x5358000
	v_readlane_b32 s1, v237, 12
	s_addc_u32 s35, s63, 0
	s_lshl_b32 s0, s2, 10
	s_lshl_b32 s1, s1, 7
	v_lshlrev_b32_e32 v41, 1, v128
	s_add_i32 s0, s0, s1
	v_or_b32_e32 v43, s0, v41
	s_lshl_b32 s70, s14, 10
	v_mov_b32_e32 v0, 0
	s_movk_i32 s71, 0x1000
	s_mov_b32 s72, 0x4300000
	s_mov_b32 s73, 0x4302000
	s_mov_b32 s74, 0x430b000
	s_mov_b32 s75, 0x430d000
	s_mov_b32 s76, 0x4316000
	s_mov_b32 s77, 0x4318000
	s_mov_b32 s78, 0x4321000
	s_mov_b32 s79, 0x4323000
	s_mov_b32 s97, 0
	s_mov_b32 s80, s34
	s_branch .LBB0_771

; __global__ void __launch_bounds__(512, 2) fwd_kernel(Args args) {
;     ...
;         for (int it = gw; it < 264 * 22; it += NGW) act_item(it, UP, HALO, args.in[I_SCONV], args.in[I_WCONV], args.in[I_BCONV], out, lane);
.LBB0_770:
	s_add_i32 s97, s97, 1
	v_readlane_b32 s0, v237, 12
	s_cmp_gt_u32 s97, 2
	s_cbranch_scc1 .LBB0_819
	s_cmp_eq_u32 s97, 1
	s_cbranch_scc1 .Lp6_second
	s_cmp_gt_u32 s0, 6
	s_cbranch_scc1 .LBB0_819
	s_mul_i32 s1, s2, 7
	s_add_i32 s1, s1, s0
	s_cmpk_gt_u32 s1, 0x6af
	s_cbranch_scc1 .LBB0_819
	s_cmpk_lt_u32 s1, 0x600
	s_cbranch_scc1 .Lp6_third_prompt
	s_sub_i32 s1, s1, 0x600
	s_lshl_b32 s1, s1, 3
	s_addk_i32 s1, 0x807
	s_branch .Lp6_go
.Lp6_third_prompt:
	s_addk_i32 s1, 0x1000
	s_branch .Lp6_go
.Lp6_second:
	s_add_i32 s1, s80, s96
	s_cmp_lg_u32 s0, 7
	s_cbranch_scc1 .Lp6_go
	s_cmpk_gt_u32 s2, 0xaf
	s_cbranch_scc1 .Lp6_go
	s_add_i32 s1, s2, 0x1600
	s_mov_b32 s97, 2
